# P2 input projection: workgroups start staggered by (blockIdx&7) x ~1us so per-XCD epilogue store bursts interleave with other XCDs K-loops
# baseline (speedup 1.0000x reference)
;     __device__ void init(int G_, int c_) { so.init(16384, 12288, G_, c_); G = G_; c = c_; }
;     __device__ bool next(int i, Unit& o) const { if (i != 0) return false; o = u; return true; }
;     __device__ bool next(int i, Unit& u) const {
;         if (so.next(i, u)) return true;
;         const long L = (long)i * G + c - 3072; if (L < 0 || L >= 160) return false;
;         u.pm = 64 + (int)(L & 7); u.pn = (int)(L >> 3); return true;
;     }
; __global__ void __launch_bounds__(512, 2) fwd_megakernel(Params p_unused) {
;     ...
;     pg8::Gemm g{H, WIN, MALL, NIN, DM, DM}; pg8::OrderIn S; S.init(G, bx);
;     pg8::EpiIn E{AK, AV, LFF, LFB, RI, AQ, RQ, RG, GATES, ctl + C_LBF, ctl + C_LBB, ctl + C_COS, ctl + C_SIN};
;     ...
;     if (rep == 1) { pg8::EpiNone EN{(float*)(ws + WS_CTL) + 200000}; pg8::gemm_phase<pg8::EpiNone, pg8::OrderIn, true, true>(glds, g, S, EN); } else
;     ...
;     pg8::gemm_phase<pg8::EpiIn, pg8::OrderIn, true, true>(glds, g, S, E);
.LBB0_159:
	s_or_b64 exec, exec, s[4:5]
	s_mov_b64 s[4:5], s[86:87]
	s_waitcnt lgkmcnt(0)
	v_mov_b32_e32 v0, v194
	v_mov_b32_e32 v8, v194
	s_barrier
	s_and_b32 s98, s96, 7
	s_cbranch_scc0 .Lskew_p2_done
.Lskew_p2_loop:
	s_sleep 32
	s_add_i32 s98, s98, -1
	s_cmp_lg_u32 s98, 0
	s_cbranch_scc1 .Lskew_p2_loop
.Lskew_p2_done:
	s_cmpk_gt_i32 s96, 0xbff
	s_nop 0
	v_readfirstlane_b32 s0, v8
	s_cbranch_scc0 .LBB0_162
	s_mov_b64 s[12:13], 0
	s_cmpk_gt_u32 s96, 0xc9f
	s_mov_b64 s[10:11], 0
	s_cbranch_scc1 .LBB0_163
	s_add_u32 s2, s96, 0xfffff400
	s_addc_u32 s3, 0, 7
	s_and_b32 s1, s96, 7
	s_lshr_b64 s[6:7], s[2:3], 3
	s_or_b32 s8, s1, 64
	s_mov_b64 s[10:11], -1
	s_branch .LBB0_163

; __global__ void __launch_bounds__(512, 2) fwd_megakernel(Params p_unused) {
	.amdhsa_kernel _Z14fwd_megakernel6Params
		.amdhsa_group_segment_fixed_size 0
		.amdhsa_private_segment_fixed_size 0
		.amdhsa_kernarg_size 464
		.amdhsa_user_sgpr_count 2
		.amdhsa_user_sgpr_dispatch_ptr 0
		.amdhsa_user_sgpr_queue_ptr 0
		.amdhsa_user_sgpr_kernarg_segment_ptr 1
		.amdhsa_user_sgpr_dispatch_id 0
		.amdhsa_user_sgpr_kernarg_preload_length 0
		.amdhsa_user_sgpr_kernarg_preload_offset 0
		.amdhsa_user_sgpr_private_segment_size 0
		.amdhsa_uses_dynamic_stack 0
		.amdhsa_enable_private_segment 0
		.amdhsa_system_sgpr_workgroup_id_x 1
		.amdhsa_system_sgpr_workgroup_id_y 0
		.amdhsa_system_sgpr_workgroup_id_z 0
		.amdhsa_system_sgpr_workgroup_info 0
		.amdhsa_system_vgpr_workitem_id 2
		.amdhsa_next_free_vgpr 248
		.amdhsa_next_free_sgpr 100
		.amdhsa_accum_offset 248
		.amdhsa_reserve_vcc 1
		.amdhsa_float_round_mode_32 0
		.amdhsa_float_round_mode_16_64 0
		.amdhsa_float_denorm_mode_32 3
		.amdhsa_float_denorm_mode_16_64 3
		.amdhsa_dx10_clamp 1
		.amdhsa_ieee_mode 1
		.amdhsa_fp16_overflow 0
		.amdhsa_tg_split 0
		.amdhsa_exception_fp_ieee_invalid_op 0
		.amdhsa_exception_fp_denorm_src 0
		.amdhsa_exception_fp_ieee_div_zero 0
		.amdhsa_exception_fp_ieee_overflow 0
		.amdhsa_exception_fp_ieee_underflow 0
		.amdhsa_exception_fp_ieee_inexact 0
		.amdhsa_exception_int_div_zero 0
	.end_amdhsa_kernel

; __global__ void __launch_bounds__(512, 2) fwd_megakernel(Params p_unused) {
amdhsa.kernels:
  - .agpr_count:     0
    .args:
      - .offset:         0
        .size:           208
        .value_kind:     by_value
      - .offset:         208
        .size:           4
        .value_kind:     hidden_block_count_x
      - .offset:         212
        .size:           4
        .value_kind:     hidden_block_count_y
      - .offset:         216
        .size:           4
        .value_kind:     hidden_block_count_z
      - .offset:         220
        .size:           2
        .value_kind:     hidden_group_size_x
      - .offset:         222
        .size:           2
        .value_kind:     hidden_group_size_y
      - .offset:         224
        .size:           2
        .value_kind:     hidden_group_size_z
      - .offset:         226
        .size:           2
        .value_kind:     hidden_remainder_x
      - .offset:         228
        .size:           2
        .value_kind:     hidden_remainder_y
      - .offset:         230
        .size:           2
        .value_kind:     hidden_remainder_z
      - .offset:         248
        .size:           8
        .value_kind:     hidden_global_offset_x
      - .offset:         256
        .size:           8
        .value_kind:     hidden_global_offset_y
      - .offset:         264
        .size:           8
        .value_kind:     hidden_global_offset_z
      - .offset:         272
        .size:           2
        .value_kind:     hidden_grid_dims
      - .offset:         296
        .size:           8
        .value_kind:     hidden_multigrid_sync_arg
      - .offset:         328
        .size:           4
        .value_kind:     hidden_dynamic_lds_size
    .group_segment_fixed_size: 0
    .kernarg_segment_align: 8
    .kernarg_segment_size: 464
    .language:       OpenCL C
    .language_version:
      - 2
      - 0
    .max_flat_workgroup_size: 512
    .name:           _Z14fwd_megakernel6Params
    .private_segment_fixed_size: 0
    .sgpr_count:     106
    .sgpr_spill_count: 34
    .symbol:         _Z14fwd_megakernel6Params.kd
    .uniform_work_group_size: 1
    .uses_dynamic_stack: false
    .vgpr_count:     248
    .vgpr_spill_count: 0
    .wavefront_size: 64
